# v81 + retention output stage rewritten straight-line: scalar-base addressing (one add per row), bf16 packs in the DPP reduction's wait slots
# speedup vs baseline: 1.0004x; 1.0004x over previous
.Lret_f_end:
	s_nop 3
	v_add_u32_e32 v1, v234, v207
	v_add_u32_e32 v10, 1, v1
	v_cvt_f32_i32_e32 v14, v10
	v_mul_f32_e32 v2, v232, v14
	v_exp_f32_e32 v4, v2
	v_lshlrev_b32_e32 v2, 3, v233
	v_mul_lo_u32 v3, v1, s68
	v_add3_u32 v5, v208, v2, v3
	v_mul_f32_e32 v2, v4, v96
	v_mul_f32_e32 v3, v4, v97
	v_cvt_pk_bf16_f32 v2, v2, v3
	v_mul_f32_e32 v3, v4, v98
	v_mul_f32_e32 v6, v4, v99
	v_cvt_pk_bf16_f32 v3, v3, v6
	v_add_u32_e32 v1, 33, v1
	ds_write_b64 v5, v[2:3] offset:34816
	v_mul_f32_e32 v2, v4, v100
	v_mul_f32_e32 v3, v4, v101
	v_cvt_f32_i32_e32 v1, v1
	v_cvt_pk_bf16_f32 v2, v2, v3
	v_mul_f32_e32 v3, v4, v102
	v_mul_f32_e32 v6, v4, v103
	v_cvt_pk_bf16_f32 v3, v3, v6
	ds_write_b64 v5, v[2:3] offset:34832
	v_mul_f32_e32 v2, v4, v104
	v_mul_f32_e32 v3, v4, v105
	v_cvt_pk_bf16_f32 v2, v2, v3
	v_mul_f32_e32 v3, v4, v106
	v_mul_f32_e32 v1, v232, v1
	v_mul_f32_e32 v6, v4, v107
	v_cvt_pk_bf16_f32 v3, v3, v6
	v_exp_f32_e32 v1, v1
	ds_write_b64 v5, v[2:3] offset:34848
	v_mul_f32_e32 v2, v4, v108
	v_mul_f32_e32 v3, v4, v109
	v_cvt_pk_bf16_f32 v2, v2, v3
	v_mul_f32_e32 v3, v4, v110
	v_mul_f32_e32 v4, v4, v111
	v_cvt_pk_bf16_f32 v3, v3, v4
	ds_write_b64 v5, v[2:3] offset:34864
	v_mul_f32_e32 v2, v1, v80
	v_mul_f32_e32 v3, v1, v81
	v_cvt_pk_bf16_f32 v2, v2, v3
	v_mul_f32_e32 v3, v1, v82
	v_mul_f32_e32 v4, v1, v83
	v_cvt_pk_bf16_f32 v3, v3, v4
	ds_write_b64 v5, v[2:3] offset:43520
	v_mul_f32_e32 v2, v1, v84
	v_mul_f32_e32 v3, v1, v85
	v_cvt_pk_bf16_f32 v2, v2, v3
	v_mul_f32_e32 v3, v1, v86
	v_mul_f32_e32 v4, v1, v87
	v_cvt_pk_bf16_f32 v3, v3, v4
	ds_write_b64 v5, v[2:3] offset:43536
	v_mul_f32_e32 v2, v1, v88
	v_mul_f32_e32 v3, v1, v89
	v_cvt_pk_bf16_f32 v2, v2, v3
	v_mul_f32_e32 v3, v1, v90
	s_add_u32 s16, s40, s28
	v_mul_f32_e32 v4, v1, v91
	v_cvt_pk_bf16_f32 v3, v3, v4
	s_addc_u32 s17, s41, s34
	ds_write_b64 v5, v[2:3] offset:43552
	v_mul_f32_e32 v2, v1, v92
	v_mul_f32_e32 v3, v1, v93
	s_lshl_b64 s[18:19], s[16:17], 12
	v_cvt_pk_bf16_f32 v2, v2, v3
	v_mul_f32_e32 v3, v1, v94
	s_or_b32 s18, s18, s80
	v_mul_f32_e32 v1, v1, v95
	v_cvt_pk_bf16_f32 v3, v3, v1
	s_add_u32 s56, s26, s18
	ds_write_b64 v5, v[2:3] offset:43568
	s_waitcnt lgkmcnt(0)
	s_barrier
	s_addc_u32 s57, s27, s19
	v_sub_u32_e32 v10, 0x7f, v197
	ds_read_b128 v[2:5], v228 offset:34816
	ds_read_b128 v[236:239], v228 offset:43520
	ds_read_b128 v[240:243], v228 offset:52224
	ds_read_b128 v[244:247], v228 offset:60928
	s_add_u32 s54, s64, s18
	s_addc_u32 s55, s65, s19
	s_lshl_b64 s[16:17], s[16:17], 5
	s_add_u32 s18, s78, s16
	s_addc_u32 s19, s79, s17
	v_lshlrev_b32_e32 v7, 1, v203
	s_and_b64 vcc, exec, s[46:47]
	s_cbranch_vccnz .Lrg_d1
	v_lshl_or_b32 v6, v197, 12, v7
	s_waitcnt lgkmcnt(3)
	global_store_dwordx4 v6, v[2:5], s[56:57]
	v_add_u32_e32 v6, 0x20000, v6
	s_waitcnt lgkmcnt(2)
	global_store_dwordx4 v6, v[236:239], s[56:57]
	v_add_u32_e32 v6, 0x20000, v6
	s_waitcnt lgkmcnt(1)
	global_store_dwordx4 v6, v[240:243], s[56:57]
	v_add_u32_e32 v6, 0x20000, v6
	s_waitcnt lgkmcnt(0)
	global_store_dwordx4 v6, v[244:247], s[56:57]
	s_branch .LBB0_891
.Lrg_d1:
	v_sub_u32_e32 v10, 0x7f, v197
	v_lshl_or_b32 v6, v10, 12, v7
	v_lshlrev_b32_e32 v9, 5, v10
	s_waitcnt lgkmcnt(3)
	v_lshlrev_b32_e32 v80, 16, v2
	v_and_b32_e32 v81, 0xffff0000, v2
	v_lshlrev_b32_e32 v82, 16, v3
	v_and_b32_e32 v83, 0xffff0000, v3
	v_lshlrev_b32_e32 v84, 16, v4
	v_and_b32_e32 v85, 0xffff0000, v4
	v_lshlrev_b32_e32 v86, 16, v5
	v_and_b32_e32 v87, 0xffff0000, v5
	s_waitcnt vmcnt(0)
	v_lshlrev_b32_e32 v88, 16, v124
	v_and_b32_e32 v89, 0xffff0000, v124
	v_lshlrev_b32_e32 v90, 16, v125
	v_and_b32_e32 v91, 0xffff0000, v125
	v_lshlrev_b32_e32 v92, 16, v126
	v_and_b32_e32 v93, 0xffff0000, v126
	v_lshlrev_b32_e32 v94, 16, v127
	v_and_b32_e32 v95, 0xffff0000, v127
	v_add_f32_e32 v80, v88, v80
	v_add_f32_e32 v81, v89, v81
	v_add_f32_e32 v82, v90, v82
	v_add_f32_e32 v83, v91, v83
	v_add_f32_e32 v84, v92, v84
	v_add_f32_e32 v85, v93, v85
	v_add_f32_e32 v86, v94, v86
	v_add_f32_e32 v87, v95, v87
	v_add_f32_e32 v88, v80, v81
	v_add_f32_e32 v89, v82, v83
	v_add_f32_e32 v90, v84, v85
	v_add_f32_e32 v91, v86, v87
	v_mul_f32_e32 v12, v80, v80
	v_mul_f32_e32 v13, v82, v82
	v_mul_f32_e32 v14, v84, v84
	v_mul_f32_e32 v15, v86, v86
	v_add_f32_e32 v88, v88, v89
	v_add_f32_e32 v90, v90, v91
	v_fmac_f32_e32 v12, v81, v81
	v_fmac_f32_e32 v13, v83, v83
	v_fmac_f32_e32 v14, v85, v85
	v_fmac_f32_e32 v15, v87, v87
	v_add_f32_e32 v92, v88, v90
	v_add_f32_e32 v12, v12, v13
	v_add_f32_e32 v14, v14, v15
	v_add_f32_e32 v93, v12, v14
	v_add_f32_dpp v92, v92, v92 quad_perm:[1,0,3,2] row_mask:0xf bank_mask:0xf
	v_cvt_pk_bf16_f32 v80, v80, v81
	v_add_f32_dpp v93, v93, v93 quad_perm:[1,0,3,2] row_mask:0xf bank_mask:0xf
	v_add_f32_dpp v92, v92, v92 quad_perm:[2,3,0,1] row_mask:0xf bank_mask:0xf
	v_cvt_pk_bf16_f32 v81, v82, v83
	v_add_f32_dpp v93, v93, v93 quad_perm:[2,3,0,1] row_mask:0xf bank_mask:0xf
	v_add_f32_dpp v92, v92, v92 row_ror:4 row_mask:0xf bank_mask:0xf
	v_cvt_pk_bf16_f32 v82, v84, v85
	v_add_f32_dpp v93, v93, v93 row_ror:4 row_mask:0xf bank_mask:0xf
	v_add_f32_dpp v92, v92, v92 row_ror:8 row_mask:0xf bank_mask:0xf
	v_cvt_pk_bf16_f32 v83, v86, v87
	v_add_f32_dpp v93, v93, v93 row_ror:8 row_mask:0xf bank_mask:0xf
	global_store_dwordx4 v6, v[80:83], s[54:55]
	s_and_saveexec_b64 s[58:59], s[8:9]
	s_cbranch_execz .Lrg_na0
	global_atomic_add_f32 v9, v92, s[18:19]
	global_atomic_add_f32 v9, v93, s[18:19] offset:4
.Lrg_na0:
	s_or_b64 exec, exec, s[58:59]
	v_add_u32_e32 v6, 0xfffe0000, v6
	v_add_u32_e32 v9, 0xfffffc00, v9
	s_waitcnt lgkmcnt(2)
	v_lshlrev_b32_e32 v80, 16, v236
	v_and_b32_e32 v81, 0xffff0000, v236
	v_lshlrev_b32_e32 v82, 16, v237
	v_and_b32_e32 v83, 0xffff0000, v237
	v_lshlrev_b32_e32 v84, 16, v238
	v_and_b32_e32 v85, 0xffff0000, v238
	v_lshlrev_b32_e32 v86, 16, v239
	v_and_b32_e32 v87, 0xffff0000, v239
	v_lshlrev_b32_e32 v88, 16, v128
	v_and_b32_e32 v89, 0xffff0000, v128
	v_lshlrev_b32_e32 v90, 16, v129
	v_and_b32_e32 v91, 0xffff0000, v129
	v_lshlrev_b32_e32 v92, 16, v130
	v_and_b32_e32 v93, 0xffff0000, v130
	v_lshlrev_b32_e32 v94, 16, v131
	v_and_b32_e32 v95, 0xffff0000, v131
	v_add_f32_e32 v80, v88, v80
	v_add_f32_e32 v81, v89, v81
	v_add_f32_e32 v82, v90, v82
	v_add_f32_e32 v83, v91, v83
	v_add_f32_e32 v84, v92, v84
	v_add_f32_e32 v85, v93, v85
	v_add_f32_e32 v86, v94, v86
	v_add_f32_e32 v87, v95, v87
	v_add_f32_e32 v88, v80, v81
	v_add_f32_e32 v89, v82, v83
	v_add_f32_e32 v90, v84, v85
	v_add_f32_e32 v91, v86, v87
	v_mul_f32_e32 v12, v80, v80
	v_mul_f32_e32 v13, v82, v82
	v_mul_f32_e32 v14, v84, v84
	v_mul_f32_e32 v15, v86, v86
	v_add_f32_e32 v88, v88, v89
	v_add_f32_e32 v90, v90, v91
	v_fmac_f32_e32 v12, v81, v81
	v_fmac_f32_e32 v13, v83, v83
	v_fmac_f32_e32 v14, v85, v85
	v_fmac_f32_e32 v15, v87, v87
	v_add_f32_e32 v92, v88, v90
	v_add_f32_e32 v12, v12, v13
	v_add_f32_e32 v14, v14, v15
	v_add_f32_e32 v93, v12, v14
	v_add_f32_dpp v92, v92, v92 quad_perm:[1,0,3,2] row_mask:0xf bank_mask:0xf
	v_cvt_pk_bf16_f32 v80, v80, v81
	v_add_f32_dpp v93, v93, v93 quad_perm:[1,0,3,2] row_mask:0xf bank_mask:0xf
	v_add_f32_dpp v92, v92, v92 quad_perm:[2,3,0,1] row_mask:0xf bank_mask:0xf
	v_cvt_pk_bf16_f32 v81, v82, v83
	v_add_f32_dpp v93, v93, v93 quad_perm:[2,3,0,1] row_mask:0xf bank_mask:0xf
	v_add_f32_dpp v92, v92, v92 row_ror:4 row_mask:0xf bank_mask:0xf
	v_cvt_pk_bf16_f32 v82, v84, v85
	v_add_f32_dpp v93, v93, v93 row_ror:4 row_mask:0xf bank_mask:0xf
	v_add_f32_dpp v92, v92, v92 row_ror:8 row_mask:0xf bank_mask:0xf
	v_cvt_pk_bf16_f32 v83, v86, v87
	v_add_f32_dpp v93, v93, v93 row_ror:8 row_mask:0xf bank_mask:0xf
	global_store_dwordx4 v6, v[80:83], s[54:55]
	s_and_saveexec_b64 s[58:59], s[8:9]
	s_cbranch_execz .Lrg_na1
	global_atomic_add_f32 v9, v92, s[18:19]
	global_atomic_add_f32 v9, v93, s[18:19] offset:4
.Lrg_na1:
	s_or_b64 exec, exec, s[58:59]
	v_add_u32_e32 v6, 0xfffe0000, v6
	v_add_u32_e32 v9, 0xfffffc00, v9
	s_waitcnt lgkmcnt(1)
	v_lshlrev_b32_e32 v80, 16, v240
	v_and_b32_e32 v81, 0xffff0000, v240
	v_lshlrev_b32_e32 v82, 16, v241
	v_and_b32_e32 v83, 0xffff0000, v241
	v_lshlrev_b32_e32 v84, 16, v242
	v_and_b32_e32 v85, 0xffff0000, v242
	v_lshlrev_b32_e32 v86, 16, v243
	v_and_b32_e32 v87, 0xffff0000, v243
	v_lshlrev_b32_e32 v88, 16, v132
	v_and_b32_e32 v89, 0xffff0000, v132
	v_lshlrev_b32_e32 v90, 16, v133
	v_and_b32_e32 v91, 0xffff0000, v133
	v_lshlrev_b32_e32 v92, 16, v134
	v_and_b32_e32 v93, 0xffff0000, v134
	v_lshlrev_b32_e32 v94, 16, v135
	v_and_b32_e32 v95, 0xffff0000, v135
	v_add_f32_e32 v80, v88, v80
	v_add_f32_e32 v81, v89, v81
	v_add_f32_e32 v82, v90, v82
	v_add_f32_e32 v83, v91, v83
	v_add_f32_e32 v84, v92, v84
	v_add_f32_e32 v85, v93, v85
	v_add_f32_e32 v86, v94, v86
	v_add_f32_e32 v87, v95, v87
	v_add_f32_e32 v88, v80, v81
	v_add_f32_e32 v89, v82, v83
	v_add_f32_e32 v90, v84, v85
	v_add_f32_e32 v91, v86, v87
	v_mul_f32_e32 v12, v80, v80
	v_mul_f32_e32 v13, v82, v82
	v_mul_f32_e32 v14, v84, v84
	v_mul_f32_e32 v15, v86, v86
	v_add_f32_e32 v88, v88, v89
	v_add_f32_e32 v90, v90, v91
	v_fmac_f32_e32 v12, v81, v81
	v_fmac_f32_e32 v13, v83, v83
	v_fmac_f32_e32 v14, v85, v85
	v_fmac_f32_e32 v15, v87, v87
	v_add_f32_e32 v92, v88, v90
	v_add_f32_e32 v12, v12, v13
	v_add_f32_e32 v14, v14, v15
	v_add_f32_e32 v93, v12, v14
	v_add_f32_dpp v92, v92, v92 quad_perm:[1,0,3,2] row_mask:0xf bank_mask:0xf
	v_cvt_pk_bf16_f32 v80, v80, v81
	v_add_f32_dpp v93, v93, v93 quad_perm:[1,0,3,2] row_mask:0xf bank_mask:0xf
	v_add_f32_dpp v92, v92, v92 quad_perm:[2,3,0,1] row_mask:0xf bank_mask:0xf
	v_cvt_pk_bf16_f32 v81, v82, v83
	v_add_f32_dpp v93, v93, v93 quad_perm:[2,3,0,1] row_mask:0xf bank_mask:0xf
	v_add_f32_dpp v92, v92, v92 row_ror:4 row_mask:0xf bank_mask:0xf
	v_cvt_pk_bf16_f32 v82, v84, v85
	v_add_f32_dpp v93, v93, v93 row_ror:4 row_mask:0xf bank_mask:0xf
	v_add_f32_dpp v92, v92, v92 row_ror:8 row_mask:0xf bank_mask:0xf
	v_cvt_pk_bf16_f32 v83, v86, v87
	v_add_f32_dpp v93, v93, v93 row_ror:8 row_mask:0xf bank_mask:0xf
	global_store_dwordx4 v6, v[80:83], s[54:55]
	s_and_saveexec_b64 s[58:59], s[8:9]
	s_cbranch_execz .Lrg_na2
	global_atomic_add_f32 v9, v92, s[18:19]
	global_atomic_add_f32 v9, v93, s[18:19] offset:4
.Lrg_na2:
	s_or_b64 exec, exec, s[58:59]
	v_add_u32_e32 v6, 0xfffe0000, v6
	v_add_u32_e32 v9, 0xfffffc00, v9
	s_waitcnt lgkmcnt(0)
	v_lshlrev_b32_e32 v80, 16, v244
	v_and_b32_e32 v81, 0xffff0000, v244
	v_lshlrev_b32_e32 v82, 16, v245
	v_and_b32_e32 v83, 0xffff0000, v245
	v_lshlrev_b32_e32 v84, 16, v246
	v_and_b32_e32 v85, 0xffff0000, v246
	v_lshlrev_b32_e32 v86, 16, v247
	v_and_b32_e32 v87, 0xffff0000, v247
	v_lshlrev_b32_e32 v88, 16, v136
	v_and_b32_e32 v89, 0xffff0000, v136
	v_lshlrev_b32_e32 v90, 16, v137
	v_and_b32_e32 v91, 0xffff0000, v137
	v_lshlrev_b32_e32 v92, 16, v138
	v_and_b32_e32 v93, 0xffff0000, v138
	v_lshlrev_b32_e32 v94, 16, v139
	v_and_b32_e32 v95, 0xffff0000, v139
	v_add_f32_e32 v80, v88, v80
	v_add_f32_e32 v81, v89, v81
	v_add_f32_e32 v82, v90, v82
	v_add_f32_e32 v83, v91, v83
	v_add_f32_e32 v84, v92, v84
	v_add_f32_e32 v85, v93, v85
	v_add_f32_e32 v86, v94, v86
	v_add_f32_e32 v87, v95, v87
	v_add_f32_e32 v88, v80, v81
	v_add_f32_e32 v89, v82, v83
	v_add_f32_e32 v90, v84, v85
	v_add_f32_e32 v91, v86, v87
	v_mul_f32_e32 v12, v80, v80
	v_mul_f32_e32 v13, v82, v82
	v_mul_f32_e32 v14, v84, v84
	v_mul_f32_e32 v15, v86, v86
	v_add_f32_e32 v88, v88, v89
	v_add_f32_e32 v90, v90, v91
	v_fmac_f32_e32 v12, v81, v81
	v_fmac_f32_e32 v13, v83, v83
	v_fmac_f32_e32 v14, v85, v85
	v_fmac_f32_e32 v15, v87, v87
	v_add_f32_e32 v92, v88, v90
	v_add_f32_e32 v12, v12, v13
	v_add_f32_e32 v14, v14, v15
	v_add_f32_e32 v93, v12, v14
	v_add_f32_dpp v92, v92, v92 quad_perm:[1,0,3,2] row_mask:0xf bank_mask:0xf
	v_cvt_pk_bf16_f32 v80, v80, v81
	v_add_f32_dpp v93, v93, v93 quad_perm:[1,0,3,2] row_mask:0xf bank_mask:0xf
	v_add_f32_dpp v92, v92, v92 quad_perm:[2,3,0,1] row_mask:0xf bank_mask:0xf
	v_cvt_pk_bf16_f32 v81, v82, v83
	v_add_f32_dpp v93, v93, v93 quad_perm:[2,3,0,1] row_mask:0xf bank_mask:0xf
	v_add_f32_dpp v92, v92, v92 row_ror:4 row_mask:0xf bank_mask:0xf
	v_cvt_pk_bf16_f32 v82, v84, v85
	v_add_f32_dpp v93, v93, v93 row_ror:4 row_mask:0xf bank_mask:0xf
	v_add_f32_dpp v92, v92, v92 row_ror:8 row_mask:0xf bank_mask:0xf
	v_cvt_pk_bf16_f32 v83, v86, v87
	v_add_f32_dpp v93, v93, v93 row_ror:8 row_mask:0xf bank_mask:0xf
	global_store_dwordx4 v6, v[80:83], s[54:55]
	s_and_saveexec_b64 s[58:59], s[8:9]
	s_cbranch_execz .Lrg_na3
	global_atomic_add_f32 v9, v92, s[18:19]
	global_atomic_add_f32 v9, v93, s[18:19] offset:4
.Lrg_na3:
	s_or_b64 exec, exec, s[58:59]
	s_branch .LBB0_891
